# combination: quad-packed ds_write_b64 staging + counted lgkmcnt waits (12/6/0) + RoPE table prefetch ordering on top of the lane-pair version
# speedup vs baseline: 1.0019x; 1.0019x over previous
.Levin1_notr:
	s_cmp_eq_u32 s24, 2
	s_cbranch_scc1 .LBB0_259
	s_cmp_eq_u32 s24, 7
	s_cbranch_scc1 .LBB0_259
	s_cmp_ge_u32 s24, 3
	s_cselect_b32 s2, 1, 0
	s_sub_u32 s2, s24, s2
	s_cmp_ge_u32 s24, 8
	s_cselect_b32 s3, 1, 0
	s_sub_u32 s2, s2, s3
	s_lshl_b32 s2, s2, 9
	s_add_u32 s2, s2, s0
	s_lshl_b32 s2, s2, 1
	s_mul_i32 s3, s1, 0x1c00
	s_add_u32 s2, s2, s3
	s_add_u32 s98, s90, 0x3971900
	s_addc_u32 s99, s91, 0
	s_add_u32 s98, s98, s2
	s_addc_u32 s99, s99, 0
	v_and_b32_e32 v120, 1, v118
	v_lshlrev_b32_e32 v121, 6, v120
	v_sub_u32_e32 v121, v121, v120
	v_sub_u32_e32 v121, v121, v120
	v_add_u32_e32 v121, v121, v112
	v_cmp_eq_u32_e32 vcc, 1, v120
	v_mov_b32_e32 v120, 0x05040100
	v_mov_b32_e32 v122, 0x03020706
	s_nop 1
	v_cndmask_b32_e32 v120, v120, v122, vcc
	v_and_b32_e32 v122, 2, v118
	v_cmp_ne_u32_e64 s[100:101], 0, v122
	v_and_b32_e32 v121, 3, v118
	v_lshlrev_b32_e32 v121, 6, v121
	v_and_b32_e32 v122, 28, v118
	v_lshl_add_u32 v121, v122, 1, v121
	v_lshrrev_b32_e32 v122, 5, v118
	v_lshl_add_u32 v121, v122, 8, v121
	v_sub_u32_e32 v122, v113, v118
	v_lshlrev_b32_e32 v123, 4, v118
	v_sub_u32_e32 v122, v113, v123
	v_add_u32_e32 v121, v121, v122
	v_cvt_pk_bf16_f32 v64, v48, v49
	v_cvt_pk_bf16_f32 v65, v50, v51
	v_cvt_pk_bf16_f32 v66, v52, v53
	v_cvt_pk_bf16_f32 v67, v54, v55
	v_cvt_pk_bf16_f32 v68, v56, v57
	v_cvt_pk_bf16_f32 v69, v58, v59
	v_cvt_pk_bf16_f32 v70, v60, v61
	v_cvt_pk_bf16_f32 v71, v62, v63
	v_mov_b32_dpp v72, v64 quad_perm:[1,0,3,2] row_mask:0xf bank_mask:0xf
	v_mov_b32_dpp v73, v65 quad_perm:[1,0,3,2] row_mask:0xf bank_mask:0xf
	v_mov_b32_dpp v74, v66 quad_perm:[1,0,3,2] row_mask:0xf bank_mask:0xf
	v_mov_b32_dpp v75, v67 quad_perm:[1,0,3,2] row_mask:0xf bank_mask:0xf
	v_mov_b32_dpp v76, v68 quad_perm:[1,0,3,2] row_mask:0xf bank_mask:0xf
	v_mov_b32_dpp v77, v69 quad_perm:[1,0,3,2] row_mask:0xf bank_mask:0xf
	v_mov_b32_dpp v78, v70 quad_perm:[1,0,3,2] row_mask:0xf bank_mask:0xf
	v_mov_b32_dpp v79, v71 quad_perm:[1,0,3,2] row_mask:0xf bank_mask:0xf
	v_perm_b32 v72, v72, v64, v120
	v_perm_b32 v73, v73, v65, v120
	v_perm_b32 v74, v74, v66, v120
	v_perm_b32 v75, v75, v67, v120
	v_perm_b32 v76, v76, v68, v120
	v_perm_b32 v77, v77, v69, v120
	v_perm_b32 v78, v78, v70, v120
	v_perm_b32 v79, v79, v71, v120
	v_mov_b32_dpp v64, v72 quad_perm:[2,3,0,1] row_mask:0xf bank_mask:0xf
	v_mov_b32_dpp v65, v73 quad_perm:[2,3,0,1] row_mask:0xf bank_mask:0xf
	v_mov_b32_dpp v66, v74 quad_perm:[2,3,0,1] row_mask:0xf bank_mask:0xf
	v_mov_b32_dpp v67, v75 quad_perm:[2,3,0,1] row_mask:0xf bank_mask:0xf
	v_mov_b32_dpp v68, v76 quad_perm:[2,3,0,1] row_mask:0xf bank_mask:0xf
	v_mov_b32_dpp v69, v77 quad_perm:[2,3,0,1] row_mask:0xf bank_mask:0xf
	v_mov_b32_dpp v70, v78 quad_perm:[2,3,0,1] row_mask:0xf bank_mask:0xf
	v_mov_b32_dpp v71, v79 quad_perm:[2,3,0,1] row_mask:0xf bank_mask:0xf
	v_cndmask_b32_e64 v72, v72, v65, s[100:101]
	v_cndmask_b32_e64 v73, v64, v73, s[100:101]
	v_cndmask_b32_e64 v74, v74, v67, s[100:101]
	v_cndmask_b32_e64 v75, v66, v75, s[100:101]
	v_cndmask_b32_e64 v76, v76, v69, s[100:101]
	v_cndmask_b32_e64 v77, v68, v77, s[100:101]
	v_cndmask_b32_e64 v78, v78, v71, s[100:101]
	v_cndmask_b32_e64 v79, v70, v79, s[100:101]
	ds_write_b64 v121, v[72:73]
	ds_write_b64 v121, v[74:75] offset:512
	ds_write_b64 v121, v[76:77] offset:1024
	ds_write_b64 v121, v[78:79] offset:1536
	ds_read_b128 v[80:83], v113
	ds_read_b128 v[84:87], v113 offset:1024
	v_cvt_pk_bf16_f32 v64, v16, v17
	v_cvt_pk_bf16_f32 v65, v18, v19
	v_cvt_pk_bf16_f32 v66, v20, v21
	v_cvt_pk_bf16_f32 v67, v22, v23
	v_cvt_pk_bf16_f32 v68, v24, v25
	v_cvt_pk_bf16_f32 v69, v26, v27
	v_cvt_pk_bf16_f32 v70, v28, v29
	v_cvt_pk_bf16_f32 v71, v30, v31
	v_mov_b32_dpp v72, v64 quad_perm:[1,0,3,2] row_mask:0xf bank_mask:0xf
	v_mov_b32_dpp v73, v65 quad_perm:[1,0,3,2] row_mask:0xf bank_mask:0xf
	v_mov_b32_dpp v74, v66 quad_perm:[1,0,3,2] row_mask:0xf bank_mask:0xf
	v_mov_b32_dpp v75, v67 quad_perm:[1,0,3,2] row_mask:0xf bank_mask:0xf
	v_mov_b32_dpp v76, v68 quad_perm:[1,0,3,2] row_mask:0xf bank_mask:0xf
	v_mov_b32_dpp v77, v69 quad_perm:[1,0,3,2] row_mask:0xf bank_mask:0xf
	v_mov_b32_dpp v78, v70 quad_perm:[1,0,3,2] row_mask:0xf bank_mask:0xf
	v_mov_b32_dpp v79, v71 quad_perm:[1,0,3,2] row_mask:0xf bank_mask:0xf
	v_perm_b32 v72, v72, v64, v120
	v_perm_b32 v73, v73, v65, v120
	v_perm_b32 v74, v74, v66, v120
	v_perm_b32 v75, v75, v67, v120
	v_perm_b32 v76, v76, v68, v120
	v_perm_b32 v77, v77, v69, v120
	v_perm_b32 v78, v78, v70, v120
	v_perm_b32 v79, v79, v71, v120
	v_mov_b32_dpp v64, v72 quad_perm:[2,3,0,1] row_mask:0xf bank_mask:0xf
	v_mov_b32_dpp v65, v73 quad_perm:[2,3,0,1] row_mask:0xf bank_mask:0xf
	v_mov_b32_dpp v66, v74 quad_perm:[2,3,0,1] row_mask:0xf bank_mask:0xf
	v_mov_b32_dpp v67, v75 quad_perm:[2,3,0,1] row_mask:0xf bank_mask:0xf
	v_mov_b32_dpp v68, v76 quad_perm:[2,3,0,1] row_mask:0xf bank_mask:0xf
	v_mov_b32_dpp v69, v77 quad_perm:[2,3,0,1] row_mask:0xf bank_mask:0xf
	v_mov_b32_dpp v70, v78 quad_perm:[2,3,0,1] row_mask:0xf bank_mask:0xf
	v_mov_b32_dpp v71, v79 quad_perm:[2,3,0,1] row_mask:0xf bank_mask:0xf
	v_cndmask_b32_e64 v72, v72, v65, s[100:101]
	v_cndmask_b32_e64 v73, v64, v73, s[100:101]
	v_cndmask_b32_e64 v74, v74, v67, s[100:101]
	v_cndmask_b32_e64 v75, v66, v75, s[100:101]
	v_cndmask_b32_e64 v76, v76, v69, s[100:101]
	v_cndmask_b32_e64 v77, v68, v77, s[100:101]
	v_cndmask_b32_e64 v78, v78, v71, s[100:101]
	v_cndmask_b32_e64 v79, v70, v79, s[100:101]
	ds_write_b64 v121, v[72:73]
	ds_write_b64 v121, v[74:75] offset:512
	ds_write_b64 v121, v[76:77] offset:1024
	ds_write_b64 v121, v[78:79] offset:1536
	ds_read_b128 v[88:91], v113
	ds_read_b128 v[92:95], v113 offset:1024
	v_cvt_pk_bf16_f32 v64, v32, v33
	v_cvt_pk_bf16_f32 v65, v34, v35
	v_cvt_pk_bf16_f32 v66, v36, v37
	v_cvt_pk_bf16_f32 v67, v38, v39
	v_cvt_pk_bf16_f32 v68, v40, v41
	v_cvt_pk_bf16_f32 v69, v42, v43
	v_cvt_pk_bf16_f32 v70, v44, v45
	v_cvt_pk_bf16_f32 v71, v46, v47
	v_mov_b32_dpp v72, v64 quad_perm:[1,0,3,2] row_mask:0xf bank_mask:0xf
	v_mov_b32_dpp v73, v65 quad_perm:[1,0,3,2] row_mask:0xf bank_mask:0xf
	v_mov_b32_dpp v74, v66 quad_perm:[1,0,3,2] row_mask:0xf bank_mask:0xf
	v_mov_b32_dpp v75, v67 quad_perm:[1,0,3,2] row_mask:0xf bank_mask:0xf
	v_mov_b32_dpp v76, v68 quad_perm:[1,0,3,2] row_mask:0xf bank_mask:0xf
	v_mov_b32_dpp v77, v69 quad_perm:[1,0,3,2] row_mask:0xf bank_mask:0xf
	v_mov_b32_dpp v78, v70 quad_perm:[1,0,3,2] row_mask:0xf bank_mask:0xf
	v_mov_b32_dpp v79, v71 quad_perm:[1,0,3,2] row_mask:0xf bank_mask:0xf
	v_perm_b32 v72, v72, v64, v120
	v_perm_b32 v73, v73, v65, v120
	v_perm_b32 v74, v74, v66, v120
	v_perm_b32 v75, v75, v67, v120
	v_perm_b32 v76, v76, v68, v120
	v_perm_b32 v77, v77, v69, v120
	v_perm_b32 v78, v78, v70, v120
	v_perm_b32 v79, v79, v71, v120
	v_mov_b32_dpp v64, v72 quad_perm:[2,3,0,1] row_mask:0xf bank_mask:0xf
	v_mov_b32_dpp v65, v73 quad_perm:[2,3,0,1] row_mask:0xf bank_mask:0xf
	v_mov_b32_dpp v66, v74 quad_perm:[2,3,0,1] row_mask:0xf bank_mask:0xf
	v_mov_b32_dpp v67, v75 quad_perm:[2,3,0,1] row_mask:0xf bank_mask:0xf
	v_mov_b32_dpp v68, v76 quad_perm:[2,3,0,1] row_mask:0xf bank_mask:0xf
	v_mov_b32_dpp v69, v77 quad_perm:[2,3,0,1] row_mask:0xf bank_mask:0xf
	v_mov_b32_dpp v70, v78 quad_perm:[2,3,0,1] row_mask:0xf bank_mask:0xf
	v_mov_b32_dpp v71, v79 quad_perm:[2,3,0,1] row_mask:0xf bank_mask:0xf
	v_cndmask_b32_e64 v72, v72, v65, s[100:101]
	v_cndmask_b32_e64 v73, v64, v73, s[100:101]
	v_cndmask_b32_e64 v74, v74, v67, s[100:101]
	v_cndmask_b32_e64 v75, v66, v75, s[100:101]
	v_cndmask_b32_e64 v76, v76, v69, s[100:101]
	v_cndmask_b32_e64 v77, v68, v77, s[100:101]
	v_cndmask_b32_e64 v78, v78, v71, s[100:101]
	v_cndmask_b32_e64 v79, v70, v79, s[100:101]
	ds_write_b64 v121, v[72:73]
	ds_write_b64 v121, v[74:75] offset:512
	ds_write_b64 v121, v[76:77] offset:1024
	ds_write_b64 v121, v[78:79] offset:1536
	ds_read_b128 v[96:99], v113
	ds_read_b128 v[100:103], v113 offset:1024
	v_cvt_pk_bf16_f32 v64, v0, v1
	v_cvt_pk_bf16_f32 v65, v2, v3
	v_cvt_pk_bf16_f32 v66, v4, v5
	v_cvt_pk_bf16_f32 v67, v6, v7
	v_cvt_pk_bf16_f32 v68, v8, v9
	v_cvt_pk_bf16_f32 v69, v10, v11
	v_cvt_pk_bf16_f32 v70, v12, v13
	v_cvt_pk_bf16_f32 v71, v14, v15
	v_mov_b32_dpp v72, v64 quad_perm:[1,0,3,2] row_mask:0xf bank_mask:0xf
	v_mov_b32_dpp v73, v65 quad_perm:[1,0,3,2] row_mask:0xf bank_mask:0xf
	v_mov_b32_dpp v74, v66 quad_perm:[1,0,3,2] row_mask:0xf bank_mask:0xf
	v_mov_b32_dpp v75, v67 quad_perm:[1,0,3,2] row_mask:0xf bank_mask:0xf
	v_mov_b32_dpp v76, v68 quad_perm:[1,0,3,2] row_mask:0xf bank_mask:0xf
	v_mov_b32_dpp v77, v69 quad_perm:[1,0,3,2] row_mask:0xf bank_mask:0xf
	v_mov_b32_dpp v78, v70 quad_perm:[1,0,3,2] row_mask:0xf bank_mask:0xf
	v_mov_b32_dpp v79, v71 quad_perm:[1,0,3,2] row_mask:0xf bank_mask:0xf
	v_perm_b32 v72, v72, v64, v120
	v_perm_b32 v73, v73, v65, v120
	v_perm_b32 v74, v74, v66, v120
	v_perm_b32 v75, v75, v67, v120
	v_perm_b32 v76, v76, v68, v120
	v_perm_b32 v77, v77, v69, v120
	v_perm_b32 v78, v78, v70, v120
	v_perm_b32 v79, v79, v71, v120
	v_mov_b32_dpp v64, v72 quad_perm:[2,3,0,1] row_mask:0xf bank_mask:0xf
	v_mov_b32_dpp v65, v73 quad_perm:[2,3,0,1] row_mask:0xf bank_mask:0xf
	v_mov_b32_dpp v66, v74 quad_perm:[2,3,0,1] row_mask:0xf bank_mask:0xf
	v_mov_b32_dpp v67, v75 quad_perm:[2,3,0,1] row_mask:0xf bank_mask:0xf
	v_mov_b32_dpp v68, v76 quad_perm:[2,3,0,1] row_mask:0xf bank_mask:0xf
	v_mov_b32_dpp v69, v77 quad_perm:[2,3,0,1] row_mask:0xf bank_mask:0xf
	v_mov_b32_dpp v70, v78 quad_perm:[2,3,0,1] row_mask:0xf bank_mask:0xf
	v_mov_b32_dpp v71, v79 quad_perm:[2,3,0,1] row_mask:0xf bank_mask:0xf
	v_cndmask_b32_e64 v72, v72, v65, s[100:101]
	v_cndmask_b32_e64 v73, v64, v73, s[100:101]
	v_cndmask_b32_e64 v74, v74, v67, s[100:101]
	v_cndmask_b32_e64 v75, v66, v75, s[100:101]
	v_cndmask_b32_e64 v76, v76, v69, s[100:101]
	v_cndmask_b32_e64 v77, v68, v77, s[100:101]
	v_cndmask_b32_e64 v78, v78, v71, s[100:101]
	v_cndmask_b32_e64 v79, v70, v79, s[100:101]
	ds_write_b64 v121, v[72:73]
	ds_write_b64 v121, v[74:75] offset:512
	ds_write_b64 v121, v[76:77] offset:1024
	ds_write_b64 v121, v[78:79] offset:1536
	ds_read_b128 v[104:107], v113
	ds_read_b128 v[108:111], v113 offset:1024
	s_waitcnt lgkmcnt(12)
	global_store_dwordx4 v114, v[80:83], s[98:99]
	s_add_u32 s100, s98, 0x1c000
	s_addc_u32 s101, s99, 0
	global_store_dwordx4 v114, v[84:87], s[100:101]
	global_store_dwordx4 v114, v[88:91], s[98:99] offset:64
	global_store_dwordx4 v114, v[92:95], s[100:101] offset:64
	s_add_u32 s98, s98, 0x38000
	s_addc_u32 s99, s99, 0
	s_waitcnt lgkmcnt(6)
	global_store_dwordx4 v114, v[96:99], s[98:99]
	s_add_u32 s100, s98, 0x1c000
	s_addc_u32 s101, s99, 0
	global_store_dwordx4 v114, v[100:103], s[100:101]
	s_waitcnt lgkmcnt(0)
	global_store_dwordx4 v114, v[104:107], s[98:99] offset:64
	global_store_dwordx4 v114, v[108:111], s[100:101] offset:64
	s_branch .LBB0_259

.Lodin4_nat:
	s_lshl_b32 s8, s7, 11
	s_add_u32 s8, s8, s9
	s_lshl_b32 s9, s6, 1
	s_add_u32 s8, s8, s9
	s_add_u32 s98, s90, s8
	s_addc_u32 s99, s91, 0
	v_and_b32_e32 v120, 1, v118
	v_lshlrev_b32_e32 v121, 6, v120
	v_sub_u32_e32 v121, v121, v120
	v_sub_u32_e32 v121, v121, v120
	v_add_u32_e32 v121, v121, v112
	v_cmp_eq_u32_e32 vcc, 1, v120
	v_mov_b32_e32 v120, 0x05040100
	v_mov_b32_e32 v122, 0x03020706
	s_nop 1
	v_cndmask_b32_e32 v120, v120, v122, vcc
	v_and_b32_e32 v122, 2, v118
	v_cmp_ne_u32_e64 s[100:101], 0, v122
	v_and_b32_e32 v121, 3, v118
	v_lshlrev_b32_e32 v121, 6, v121
	v_and_b32_e32 v122, 28, v118
	v_lshl_add_u32 v121, v122, 1, v121
	v_lshrrev_b32_e32 v122, 5, v118
	v_lshl_add_u32 v121, v122, 8, v121
	v_sub_u32_e32 v122, v113, v118
	v_lshlrev_b32_e32 v123, 4, v118
	v_sub_u32_e32 v122, v113, v123
	v_add_u32_e32 v121, v121, v122
	v_cvt_pk_bf16_f32 v64, v48, v49
	v_cvt_pk_bf16_f32 v65, v50, v51
	v_cvt_pk_bf16_f32 v66, v52, v53
	v_cvt_pk_bf16_f32 v67, v54, v55
	v_cvt_pk_bf16_f32 v68, v56, v57
	v_cvt_pk_bf16_f32 v69, v58, v59
	v_cvt_pk_bf16_f32 v70, v60, v61
	v_cvt_pk_bf16_f32 v71, v62, v63
	v_mov_b32_dpp v72, v64 quad_perm:[1,0,3,2] row_mask:0xf bank_mask:0xf
	v_mov_b32_dpp v73, v65 quad_perm:[1,0,3,2] row_mask:0xf bank_mask:0xf
	v_mov_b32_dpp v74, v66 quad_perm:[1,0,3,2] row_mask:0xf bank_mask:0xf
	v_mov_b32_dpp v75, v67 quad_perm:[1,0,3,2] row_mask:0xf bank_mask:0xf
	v_mov_b32_dpp v76, v68 quad_perm:[1,0,3,2] row_mask:0xf bank_mask:0xf
	v_mov_b32_dpp v77, v69 quad_perm:[1,0,3,2] row_mask:0xf bank_mask:0xf
	v_mov_b32_dpp v78, v70 quad_perm:[1,0,3,2] row_mask:0xf bank_mask:0xf
	v_mov_b32_dpp v79, v71 quad_perm:[1,0,3,2] row_mask:0xf bank_mask:0xf
	v_perm_b32 v72, v72, v64, v120
	v_perm_b32 v73, v73, v65, v120
	v_perm_b32 v74, v74, v66, v120
	v_perm_b32 v75, v75, v67, v120
	v_perm_b32 v76, v76, v68, v120
	v_perm_b32 v77, v77, v69, v120
	v_perm_b32 v78, v78, v70, v120
	v_perm_b32 v79, v79, v71, v120
	v_mov_b32_dpp v64, v72 quad_perm:[2,3,0,1] row_mask:0xf bank_mask:0xf
	v_mov_b32_dpp v65, v73 quad_perm:[2,3,0,1] row_mask:0xf bank_mask:0xf
	v_mov_b32_dpp v66, v74 quad_perm:[2,3,0,1] row_mask:0xf bank_mask:0xf
	v_mov_b32_dpp v67, v75 quad_perm:[2,3,0,1] row_mask:0xf bank_mask:0xf
	v_mov_b32_dpp v68, v76 quad_perm:[2,3,0,1] row_mask:0xf bank_mask:0xf
	v_mov_b32_dpp v69, v77 quad_perm:[2,3,0,1] row_mask:0xf bank_mask:0xf
	v_mov_b32_dpp v70, v78 quad_perm:[2,3,0,1] row_mask:0xf bank_mask:0xf
	v_mov_b32_dpp v71, v79 quad_perm:[2,3,0,1] row_mask:0xf bank_mask:0xf
	v_cndmask_b32_e64 v72, v72, v65, s[100:101]
	v_cndmask_b32_e64 v73, v64, v73, s[100:101]
	v_cndmask_b32_e64 v74, v74, v67, s[100:101]
	v_cndmask_b32_e64 v75, v66, v75, s[100:101]
	v_cndmask_b32_e64 v76, v76, v69, s[100:101]
	v_cndmask_b32_e64 v77, v68, v77, s[100:101]
	v_cndmask_b32_e64 v78, v78, v71, s[100:101]
	v_cndmask_b32_e64 v79, v70, v79, s[100:101]
	ds_write_b64 v121, v[72:73]
	ds_write_b64 v121, v[74:75] offset:512
	ds_write_b64 v121, v[76:77] offset:1024
	ds_write_b64 v121, v[78:79] offset:1536
	ds_read_b128 v[80:83], v113
	ds_read_b128 v[84:87], v113 offset:1024
	v_cvt_pk_bf16_f32 v64, v16, v17
	v_cvt_pk_bf16_f32 v65, v18, v19
	v_cvt_pk_bf16_f32 v66, v20, v21
	v_cvt_pk_bf16_f32 v67, v22, v23
	v_cvt_pk_bf16_f32 v68, v24, v25
	v_cvt_pk_bf16_f32 v69, v26, v27
	v_cvt_pk_bf16_f32 v70, v28, v29
	v_cvt_pk_bf16_f32 v71, v30, v31
	v_mov_b32_dpp v72, v64 quad_perm:[1,0,3,2] row_mask:0xf bank_mask:0xf
	v_mov_b32_dpp v73, v65 quad_perm:[1,0,3,2] row_mask:0xf bank_mask:0xf
	v_mov_b32_dpp v74, v66 quad_perm:[1,0,3,2] row_mask:0xf bank_mask:0xf
	v_mov_b32_dpp v75, v67 quad_perm:[1,0,3,2] row_mask:0xf bank_mask:0xf
	v_mov_b32_dpp v76, v68 quad_perm:[1,0,3,2] row_mask:0xf bank_mask:0xf
	v_mov_b32_dpp v77, v69 quad_perm:[1,0,3,2] row_mask:0xf bank_mask:0xf
	v_mov_b32_dpp v78, v70 quad_perm:[1,0,3,2] row_mask:0xf bank_mask:0xf
	v_mov_b32_dpp v79, v71 quad_perm:[1,0,3,2] row_mask:0xf bank_mask:0xf
	v_perm_b32 v72, v72, v64, v120
	v_perm_b32 v73, v73, v65, v120
	v_perm_b32 v74, v74, v66, v120
	v_perm_b32 v75, v75, v67, v120
	v_perm_b32 v76, v76, v68, v120
	v_perm_b32 v77, v77, v69, v120
	v_perm_b32 v78, v78, v70, v120
	v_perm_b32 v79, v79, v71, v120
	v_mov_b32_dpp v64, v72 quad_perm:[2,3,0,1] row_mask:0xf bank_mask:0xf
	v_mov_b32_dpp v65, v73 quad_perm:[2,3,0,1] row_mask:0xf bank_mask:0xf
	v_mov_b32_dpp v66, v74 quad_perm:[2,3,0,1] row_mask:0xf bank_mask:0xf
	v_mov_b32_dpp v67, v75 quad_perm:[2,3,0,1] row_mask:0xf bank_mask:0xf
	v_mov_b32_dpp v68, v76 quad_perm:[2,3,0,1] row_mask:0xf bank_mask:0xf
	v_mov_b32_dpp v69, v77 quad_perm:[2,3,0,1] row_mask:0xf bank_mask:0xf
	v_mov_b32_dpp v70, v78 quad_perm:[2,3,0,1] row_mask:0xf bank_mask:0xf
	v_mov_b32_dpp v71, v79 quad_perm:[2,3,0,1] row_mask:0xf bank_mask:0xf
	v_cndmask_b32_e64 v72, v72, v65, s[100:101]
	v_cndmask_b32_e64 v73, v64, v73, s[100:101]
	v_cndmask_b32_e64 v74, v74, v67, s[100:101]
	v_cndmask_b32_e64 v75, v66, v75, s[100:101]
	v_cndmask_b32_e64 v76, v76, v69, s[100:101]
	v_cndmask_b32_e64 v77, v68, v77, s[100:101]
	v_cndmask_b32_e64 v78, v78, v71, s[100:101]
	v_cndmask_b32_e64 v79, v70, v79, s[100:101]
	ds_write_b64 v121, v[72:73]
	ds_write_b64 v121, v[74:75] offset:512
	ds_write_b64 v121, v[76:77] offset:1024
	ds_write_b64 v121, v[78:79] offset:1536
	ds_read_b128 v[88:91], v113
	ds_read_b128 v[92:95], v113 offset:1024
	v_cvt_pk_bf16_f32 v64, v32, v33
	v_cvt_pk_bf16_f32 v65, v34, v35
	v_cvt_pk_bf16_f32 v66, v36, v37
	v_cvt_pk_bf16_f32 v67, v38, v39
	v_cvt_pk_bf16_f32 v68, v40, v41
	v_cvt_pk_bf16_f32 v69, v42, v43
	v_cvt_pk_bf16_f32 v70, v44, v45
	v_cvt_pk_bf16_f32 v71, v46, v47
	v_mov_b32_dpp v72, v64 quad_perm:[1,0,3,2] row_mask:0xf bank_mask:0xf
	v_mov_b32_dpp v73, v65 quad_perm:[1,0,3,2] row_mask:0xf bank_mask:0xf
	v_mov_b32_dpp v74, v66 quad_perm:[1,0,3,2] row_mask:0xf bank_mask:0xf
	v_mov_b32_dpp v75, v67 quad_perm:[1,0,3,2] row_mask:0xf bank_mask:0xf
	v_mov_b32_dpp v76, v68 quad_perm:[1,0,3,2] row_mask:0xf bank_mask:0xf
	v_mov_b32_dpp v77, v69 quad_perm:[1,0,3,2] row_mask:0xf bank_mask:0xf
	v_mov_b32_dpp v78, v70 quad_perm:[1,0,3,2] row_mask:0xf bank_mask:0xf
	v_mov_b32_dpp v79, v71 quad_perm:[1,0,3,2] row_mask:0xf bank_mask:0xf
	v_perm_b32 v72, v72, v64, v120
	v_perm_b32 v73, v73, v65, v120
	v_perm_b32 v74, v74, v66, v120
	v_perm_b32 v75, v75, v67, v120
	v_perm_b32 v76, v76, v68, v120
	v_perm_b32 v77, v77, v69, v120
	v_perm_b32 v78, v78, v70, v120
	v_perm_b32 v79, v79, v71, v120
	v_mov_b32_dpp v64, v72 quad_perm:[2,3,0,1] row_mask:0xf bank_mask:0xf
	v_mov_b32_dpp v65, v73 quad_perm:[2,3,0,1] row_mask:0xf bank_mask:0xf
	v_mov_b32_dpp v66, v74 quad_perm:[2,3,0,1] row_mask:0xf bank_mask:0xf
	v_mov_b32_dpp v67, v75 quad_perm:[2,3,0,1] row_mask:0xf bank_mask:0xf
	v_mov_b32_dpp v68, v76 quad_perm:[2,3,0,1] row_mask:0xf bank_mask:0xf
	v_mov_b32_dpp v69, v77 quad_perm:[2,3,0,1] row_mask:0xf bank_mask:0xf
	v_mov_b32_dpp v70, v78 quad_perm:[2,3,0,1] row_mask:0xf bank_mask:0xf
	v_mov_b32_dpp v71, v79 quad_perm:[2,3,0,1] row_mask:0xf bank_mask:0xf
	v_cndmask_b32_e64 v72, v72, v65, s[100:101]
	v_cndmask_b32_e64 v73, v64, v73, s[100:101]
	v_cndmask_b32_e64 v74, v74, v67, s[100:101]
	v_cndmask_b32_e64 v75, v66, v75, s[100:101]
	v_cndmask_b32_e64 v76, v76, v69, s[100:101]
	v_cndmask_b32_e64 v77, v68, v77, s[100:101]
	v_cndmask_b32_e64 v78, v78, v71, s[100:101]
	v_cndmask_b32_e64 v79, v70, v79, s[100:101]
	ds_write_b64 v121, v[72:73]
	ds_write_b64 v121, v[74:75] offset:512
	ds_write_b64 v121, v[76:77] offset:1024
	ds_write_b64 v121, v[78:79] offset:1536
	ds_read_b128 v[96:99], v113
	ds_read_b128 v[100:103], v113 offset:1024
	v_cvt_pk_bf16_f32 v64, v0, v1
	v_cvt_pk_bf16_f32 v65, v2, v3
	v_cvt_pk_bf16_f32 v66, v4, v5
	v_cvt_pk_bf16_f32 v67, v6, v7
	v_cvt_pk_bf16_f32 v68, v8, v9
	v_cvt_pk_bf16_f32 v69, v10, v11
	v_cvt_pk_bf16_f32 v70, v12, v13
	v_cvt_pk_bf16_f32 v71, v14, v15
	v_mov_b32_dpp v72, v64 quad_perm:[1,0,3,2] row_mask:0xf bank_mask:0xf
	v_mov_b32_dpp v73, v65 quad_perm:[1,0,3,2] row_mask:0xf bank_mask:0xf
	v_mov_b32_dpp v74, v66 quad_perm:[1,0,3,2] row_mask:0xf bank_mask:0xf
	v_mov_b32_dpp v75, v67 quad_perm:[1,0,3,2] row_mask:0xf bank_mask:0xf
	v_mov_b32_dpp v76, v68 quad_perm:[1,0,3,2] row_mask:0xf bank_mask:0xf
	v_mov_b32_dpp v77, v69 quad_perm:[1,0,3,2] row_mask:0xf bank_mask:0xf
	v_mov_b32_dpp v78, v70 quad_perm:[1,0,3,2] row_mask:0xf bank_mask:0xf
	v_mov_b32_dpp v79, v71 quad_perm:[1,0,3,2] row_mask:0xf bank_mask:0xf
	v_perm_b32 v72, v72, v64, v120
	v_perm_b32 v73, v73, v65, v120
	v_perm_b32 v74, v74, v66, v120
	v_perm_b32 v75, v75, v67, v120
	v_perm_b32 v76, v76, v68, v120
	v_perm_b32 v77, v77, v69, v120
	v_perm_b32 v78, v78, v70, v120
	v_perm_b32 v79, v79, v71, v120
	v_mov_b32_dpp v64, v72 quad_perm:[2,3,0,1] row_mask:0xf bank_mask:0xf
	v_mov_b32_dpp v65, v73 quad_perm:[2,3,0,1] row_mask:0xf bank_mask:0xf
	v_mov_b32_dpp v66, v74 quad_perm:[2,3,0,1] row_mask:0xf bank_mask:0xf
	v_mov_b32_dpp v67, v75 quad_perm:[2,3,0,1] row_mask:0xf bank_mask:0xf
	v_mov_b32_dpp v68, v76 quad_perm:[2,3,0,1] row_mask:0xf bank_mask:0xf
	v_mov_b32_dpp v69, v77 quad_perm:[2,3,0,1] row_mask:0xf bank_mask:0xf
	v_mov_b32_dpp v70, v78 quad_perm:[2,3,0,1] row_mask:0xf bank_mask:0xf
	v_mov_b32_dpp v71, v79 quad_perm:[2,3,0,1] row_mask:0xf bank_mask:0xf
	v_cndmask_b32_e64 v72, v72, v65, s[100:101]
	v_cndmask_b32_e64 v73, v64, v73, s[100:101]
	v_cndmask_b32_e64 v74, v74, v67, s[100:101]
	v_cndmask_b32_e64 v75, v66, v75, s[100:101]
	v_cndmask_b32_e64 v76, v76, v69, s[100:101]
	v_cndmask_b32_e64 v77, v68, v77, s[100:101]
	v_cndmask_b32_e64 v78, v78, v71, s[100:101]
	v_cndmask_b32_e64 v79, v70, v79, s[100:101]
	ds_write_b64 v121, v[72:73]
	ds_write_b64 v121, v[74:75] offset:512
	ds_write_b64 v121, v[76:77] offset:1024
	ds_write_b64 v121, v[78:79] offset:1536
	ds_read_b128 v[104:107], v113
	ds_read_b128 v[108:111], v113 offset:1024
	s_waitcnt lgkmcnt(12)
	global_store_dwordx4 v114, v[80:83], s[98:99]
	s_add_u32 s100, s98, 0x8000
	s_addc_u32 s101, s99, 0
	global_store_dwordx4 v114, v[84:87], s[100:101]
	global_store_dwordx4 v114, v[88:91], s[98:99] offset:64
	global_store_dwordx4 v114, v[92:95], s[100:101] offset:64
	s_add_u32 s98, s98, 0x10000
	s_addc_u32 s99, s99, 0
	s_waitcnt lgkmcnt(6)
	global_store_dwordx4 v114, v[96:99], s[98:99]
	s_add_u32 s100, s98, 0x8000
	s_addc_u32 s101, s99, 0
	global_store_dwordx4 v114, v[100:103], s[100:101]
	s_waitcnt lgkmcnt(0)
	global_store_dwordx4 v114, v[104:107], s[98:99] offset:64
	global_store_dwordx4 v114, v[108:111], s[100:101] offset:64
	s_branch .Lodin4_next
